# counted waits: exact per-MFMA lgkmcnt (3,2,1,0) for the four post-barrier K fragments in mode-0 BAR steps
# speedup vs baseline: 1.0060x; 1.0006x over previous
.LBB0_641:
	s_add_i32 s24, s23, -7
	s_lshl_b32 s92, s24, 13
	s_add_u32 vcc_lo, s100, s92
	s_addc_u32 vcc_hi, s101, 0
	global_load_dwordx4 v[52:55], v248, vcc
	s_add_i32 s24, s23, -8
	s_lshl_b32 s92, s24, 7
	s_add_u32 vcc_lo, s98, s92
	s_addc_u32 vcc_hi, s99, 0
	global_load_dwordx4 v[56:59], v249, vcc
	s_mul_i32 s26, s25, 0x2400
	s_add_i32 s24, s23, -7
	s_add_i32 s27, s26, 0xffffdc00
	s_cmp_lg_u32 s25, 0
	s_cselect_b32 s27, s27, 0x9000
	v_add_u32_e32 v1, s27, v163
	ds_read_b128 v[60:63], v1 offset:36864
	ds_read_b128 v[114:117], v1 offset:36896
	ds_read_b128 v[118:121], v1 offset:41472
	ds_read_b128 v[134:137], v1 offset:41504
	ds_read_b128 v[146:149], v1 offset:36928
	ds_read_b128 v[150:153], v1 offset:36960
	ds_read_b128 v[196:199], v1 offset:41536
	ds_read_b128 v[200:203], v1 offset:41568
	s_setprio 3
	v_cvt_pk_bf16_f32 v204, v102, v103
	v_cvt_pk_bf16_f32 v205, v104, v105
	v_cvt_pk_bf16_f32 v206, v98, v99
	v_cvt_pk_bf16_f32 v207, v100, v101
	s_waitcnt lgkmcnt(7)
	s_nop 0
	v_mfma_f32_32x32x16_bf16 v[18:33], v[60:63], v[204:207], v[18:33]
	v_add_f32_e32 v1, v102, v103
	v_add_f32_e32 v1, v1, v104
	v_add_f32_e32 v1, v1, v105
	s_waitcnt lgkmcnt(5)
	v_mfma_f32_32x32x16_bf16 v[2:17], v[118:121], v[204:207], v[2:17]
	v_cvt_pk_bf16_f32 v60, v194, v187
	v_cvt_pk_bf16_f32 v61, v186, v185
	v_cvt_pk_bf16_f32 v62, v133, v132
	v_cvt_pk_bf16_f32 v63, v131, v130
	v_add_f32_e32 v1, v1, v98
	v_add_f32_e32 v1, v1, v99
	v_add_f32_e32 v1, v1, v100
	v_add_f32_e32 v1, v1, v101
	s_nop 0
	v_mfma_f32_32x32x16_bf16 v[18:33], v[114:117], v[60:63], v[18:33]
	v_add_f32_e32 v1, v1, v194
	v_add_f32_e32 v1, v1, v187
	v_add_f32_e32 v1, v1, v186
	v_add_f32_e32 v1, v1, v185
	s_waitcnt lgkmcnt(4)
	v_mfma_f32_32x32x16_bf16 v[2:17], v[134:137], v[60:63], v[2:17]
	v_cvt_pk_bf16_f32 v98, v129, v128
	v_cvt_pk_bf16_f32 v99, v127, v126
	v_cvt_pk_bf16_f32 v100, v125, v124
	v_cvt_pk_bf16_f32 v101, v123, v122
	v_add_f32_e32 v1, v1, v133
	v_add_f32_e32 v1, v1, v132
	v_add_f32_e32 v1, v1, v131
	v_add_f32_e32 v1, v1, v130
	s_waitcnt lgkmcnt(3)
	v_mfma_f32_32x32x16_bf16 v[18:33], v[146:149], v[98:101], v[18:33]
	v_add_f32_e32 v1, v1, v129
	v_add_f32_e32 v1, v1, v128
	v_add_f32_e32 v1, v1, v127
	v_add_f32_e32 v1, v1, v126
	s_waitcnt lgkmcnt(1)
	v_mfma_f32_32x32x16_bf16 v[2:17], v[196:199], v[98:101], v[2:17]
	v_cvt_pk_bf16_f32 v60, v109, v108
	v_cvt_pk_bf16_f32 v61, v107, v106
	v_cvt_pk_bf16_f32 v62, v113, v112
	v_cvt_pk_bf16_f32 v63, v111, v110
	v_add_f32_e32 v1, v1, v125
	v_add_f32_e32 v1, v1, v124
	v_add_f32_e32 v1, v1, v123
	v_add_f32_e32 v1, v1, v122
	s_nop 0
	v_mfma_f32_32x32x16_bf16 v[18:33], v[150:153], v[60:63], v[18:33]
	v_add_f32_e32 v1, v1, v109
	v_add_f32_e32 v1, v1, v108
	v_add_f32_e32 v1, v1, v107
	v_add_f32_e32 v1, v1, v106
	s_waitcnt lgkmcnt(0)
	v_mfma_f32_32x32x16_bf16 v[2:17], v[200:203], v[60:63], v[2:17]
	v_add_f32_e32 v1, v1, v113
	v_add_f32_e32 v1, v1, v112
	v_add_f32_e32 v1, v1, v111
	v_add_f32_e32 v1, v1, v110
	s_setprio 2
	s_waitcnt lgkmcnt(0)
	s_barrier
	ds_read_b128 v[240:243], v165 offset:18432
	ds_read_b128 v[244:247], v165 offset:23040
	ds_read_b128 v[130:133], v165 offset:18464
	ds_read_b128 v[146:149], v165 offset:23072
	v_exp_f32_e32 v185, v82
	v_exp_f32_e32 v186, v83
	v_exp_f32_e32 v187, v84
	v_exp_f32_e32 v194, v85
	v_exp_f32_e32 v195, v86
	v_exp_f32_e32 v196, v87
	v_exp_f32_e32 v197, v88
	v_exp_f32_e32 v198, v89
	s_waitcnt lgkmcnt(3)
	v_mfma_f32_32x32x16_bf16 v[114:129], v[240:243], v[158:161], v[34:49]
	s_waitcnt lgkmcnt(2)
	v_mfma_f32_32x32x16_bf16 v[98:113], v[244:247], v[158:161], v[34:49]
	v_exp_f32_e32 v199, v90
	v_exp_f32_e32 v200, v91
	v_exp_f32_e32 v201, v92
	v_exp_f32_e32 v202, v93
	v_exp_f32_e32 v134, v94
	v_exp_f32_e32 v135, v95
	v_exp_f32_e32 v136, v96
	v_exp_f32_e32 v137, v97
	s_waitcnt lgkmcnt(1)
	v_mfma_f32_32x32x16_bf16 v[114:129], v[130:133], v[154:157], v[114:129]
	v_exp_f32_e32 v96, v66
	v_exp_f32_e32 v97, v67
	v_exp_f32_e32 v203, v68
	v_exp_f32_e32 v204, v69
	v_exp_f32_e32 v130, v70
	v_exp_f32_e32 v131, v71
	v_exp_f32_e32 v132, v72
	v_exp_f32_e32 v133, v73
	s_waitcnt lgkmcnt(0)
	v_mfma_f32_32x32x16_bf16 v[98:113], v[146:149], v[154:157], v[98:113]
	v_exp_f32_e32 v205, v74
	v_exp_f32_e32 v206, v75
	v_exp_f32_e32 v207, v76
	v_exp_f32_e32 v208, v77
	v_exp_f32_e32 v209, v78
	v_exp_f32_e32 v210, v79
	v_exp_f32_e32 v211, v80
	v_exp_f32_e32 v212, v81
	v_add_u32_e32 v88, s26, v163
	ds_read_b128 v[240:243], v165 offset:27648
	ds_read_b128 v[244:247], v165 offset:32256
	ds_read_b128 v[60:63], v88 offset:41472
	ds_read_b128 v[64:67], v88 offset:36864
	ds_read_b128 v[68:71], v88 offset:36896
	ds_read_b128 v[72:75], v88 offset:41504
	ds_read_b128 v[76:79], v88 offset:36928
	ds_read_b128 v[80:83], v88 offset:41536
	ds_read_b128 v[84:87], v88 offset:36960
	ds_read_b128 v[88:91], v88 offset:41568
	s_cmp_gt_i32 s25, 2
	s_cselect_b32 s27, -3, 2
	s_add_i32 s27, s27, s25
	s_add_i32 s26, s23, -6
	s_mulk_i32 s27, 0x2400
	s_min_u32 s26, s26, s13
	v_add_u32_e32 v51, s27, v182
	s_min_u32 s24, s24, s13
	s_lshl_b32 s92, s26, 13
	s_waitcnt vmcnt(3)
	ds_write_b128 v182, v[138:141]
	s_waitcnt vmcnt(2)
	ds_write_b128 v51, v[142:145] offset:36864
	v_add_f32_e32 v1, v50, v1
	s_add_u32 vcc_lo, s100, s92
	s_addc_u32 vcc_hi, s101, 0
	global_load_dwordx4 v[146:149], v248, vcc
	s_lshl_b32 s92, s24, 7
	s_add_u32 vcc_lo, s98, s92
	s_addc_u32 vcc_hi, s99, 0
	global_load_dwordx4 v[150:153], v249, vcc
	s_add_i32 s27, s25, 1
	s_setprio 1
	v_cvt_pk_bf16_f32 v92, v185, v186
	v_cvt_pk_bf16_f32 v93, v187, v194
	v_cvt_pk_bf16_f32 v94, v195, v196
	v_cvt_pk_bf16_f32 v95, v197, v198
	s_waitcnt lgkmcnt(8)
	s_nop 0
	v_mfma_f32_32x32x16_bf16 v[18:33], v[64:67], v[92:95], v[18:33]
	v_add_f32_e32 v213, v185, v186
	v_add_f32_e32 v213, v213, v187
	v_add_f32_e32 v213, v213, v194
	s_nop 0
	v_mfma_f32_32x32x16_bf16 v[2:17], v[60:63], v[92:95], v[2:17]
	v_cvt_pk_bf16_f32 v64, v199, v200
	v_cvt_pk_bf16_f32 v65, v201, v202
	v_cvt_pk_bf16_f32 v66, v134, v135
	v_cvt_pk_bf16_f32 v67, v136, v137
	v_add_f32_e32 v213, v213, v195
	v_add_f32_e32 v213, v213, v196
	v_add_f32_e32 v213, v213, v197
	v_add_f32_e32 v213, v213, v198
	s_waitcnt lgkmcnt(7)
	v_mfma_f32_32x32x16_bf16 v[18:33], v[68:71], v[64:67], v[18:33]
	v_add_f32_e32 v213, v213, v199
	v_add_f32_e32 v213, v213, v200
	v_add_f32_e32 v213, v213, v201
	v_add_f32_e32 v213, v213, v202
	s_waitcnt lgkmcnt(6)
	v_mfma_f32_32x32x16_bf16 v[2:17], v[72:75], v[64:67], v[2:17]
	v_cvt_pk_bf16_f32 v60, v96, v97
	v_cvt_pk_bf16_f32 v61, v203, v204
	v_cvt_pk_bf16_f32 v62, v130, v131
	v_cvt_pk_bf16_f32 v63, v132, v133
	v_add_f32_e32 v213, v213, v134
	v_add_f32_e32 v213, v213, v135
	v_add_f32_e32 v213, v213, v136
	v_add_f32_e32 v213, v213, v137
	s_waitcnt lgkmcnt(5)
	v_mfma_f32_32x32x16_bf16 v[18:33], v[76:79], v[60:63], v[18:33]
	v_add_f32_e32 v213, v213, v96
	v_add_f32_e32 v213, v213, v97
	v_add_f32_e32 v213, v213, v203
	v_add_f32_e32 v213, v213, v204
	s_waitcnt lgkmcnt(4)
	v_mfma_f32_32x32x16_bf16 v[2:17], v[80:83], v[60:63], v[2:17]
	v_cvt_pk_bf16_f32 v64, v205, v206
	v_cvt_pk_bf16_f32 v65, v207, v208
	v_cvt_pk_bf16_f32 v66, v209, v210
	v_cvt_pk_bf16_f32 v67, v211, v212
	v_add_f32_e32 v213, v213, v130
	v_add_f32_e32 v213, v213, v131
	v_add_f32_e32 v213, v213, v132
	v_add_f32_e32 v213, v213, v133
	s_waitcnt lgkmcnt(3)
	v_mfma_f32_32x32x16_bf16 v[18:33], v[84:87], v[64:67], v[18:33]
	v_add_f32_e32 v213, v213, v205
	v_add_f32_e32 v213, v213, v206
	v_add_f32_e32 v213, v213, v207
	v_add_f32_e32 v213, v213, v208
	s_waitcnt lgkmcnt(2)
	v_mfma_f32_32x32x16_bf16 v[2:17], v[88:91], v[64:67], v[2:17]
	v_add_f32_e32 v213, v213, v209
	v_add_f32_e32 v213, v213, v210
	v_add_f32_e32 v213, v213, v211
	v_add_f32_e32 v213, v213, v212
	s_setprio 0
	ds_read_b128 v[64:67], v165 offset:27680
	ds_read_b128 v[72:75], v165 offset:32288
	s_cmp_lg_u32 s25, 4
	s_cselect_b32 s24, s27, 0
	s_waitcnt lgkmcnt(2)
	v_mfma_f32_32x32x16_bf16 v[130:145], v[240:243], v[158:161], v[34:49]
	v_exp_f32_e32 v185, v114
	v_exp_f32_e32 v186, v115
	v_exp_f32_e32 v187, v116
	v_exp_f32_e32 v194, v117
	v_exp_f32_e32 v195, v118
	v_exp_f32_e32 v196, v119
	v_exp_f32_e32 v197, v120
	v_exp_f32_e32 v198, v121
	s_waitcnt lgkmcnt(1)
	v_mfma_f32_32x32x16_bf16 v[82:97], v[244:247], v[158:161], v[34:49]
	v_exp_f32_e32 v199, v122
	v_exp_f32_e32 v200, v123
	v_exp_f32_e32 v201, v124
	v_exp_f32_e32 v202, v125
	v_exp_f32_e32 v122, v126
	v_exp_f32_e32 v123, v127
	v_exp_f32_e32 v124, v128
	v_exp_f32_e32 v125, v129
	v_mfma_f32_32x32x16_bf16 v[130:145], v[64:67], v[154:157], v[130:145]
	v_exp_f32_e32 v126, v98
	v_exp_f32_e32 v127, v99
	v_exp_f32_e32 v128, v100
	v_exp_f32_e32 v129, v101
	v_exp_f32_e32 v203, v102
	v_exp_f32_e32 v204, v103
	v_exp_f32_e32 v205, v104
	v_exp_f32_e32 v206, v105
	s_waitcnt lgkmcnt(0)
	v_mfma_f32_32x32x16_bf16 v[82:97], v[72:75], v[154:157], v[82:97]
	v_exp_f32_e32 v102, v106
	v_exp_f32_e32 v103, v107
	v_exp_f32_e32 v104, v108
	v_exp_f32_e32 v105, v109
	v_exp_f32_e32 v106, v110
	v_exp_f32_e32 v107, v111
	v_exp_f32_e32 v108, v112
	v_exp_f32_e32 v109, v113
	s_cmp_gt_i32 s24, 2
	s_cselect_b32 s25, -3, 2
	s_add_i32 s25, s25, s24
	s_mulk_i32 s25, 0x2400
	v_add_u32_e32 v50, s25, v182
	s_add_i32 s25, s24, 1
	s_cmp_lg_u32 s24, 4
	s_cselect_b32 s24, s25, 0
	s_add_i32 s25, s23, -5
	s_min_u32 s25, s25, s13
	s_lshl_b32 s92, s25, 13
	s_waitcnt vmcnt(3)
	ds_write_b128 v182, v[52:55] offset:9216
	s_waitcnt vmcnt(2)
	ds_write_b128 v50, v[56:59] offset:36864
	s_add_u32 vcc_lo, s100, s92
	s_addc_u32 vcc_hi, s101, 0
	global_load_dwordx4 v[118:121], v248, vcc
	s_lshl_b32 s92, s26, 7
	s_add_u32 vcc_lo, s98, s92
	s_addc_u32 vcc_hi, s99, 0
	global_load_dwordx4 v[114:117], v249, vcc
	s_mul_i32 s26, s24, 0x2400
	s_add_i32 s27, s26, 0xffffdc00
	s_cmp_lg_u32 s24, 0
	s_cselect_b32 s27, s27, 0x9000
	v_add_u32_e32 v78, s27, v163
	ds_read_b128 v[50:53], v78 offset:36864
	ds_read_b128 v[54:57], v78 offset:36896
	ds_read_b128 v[58:61], v78 offset:41472
	ds_read_b128 v[62:65], v78 offset:41504
	ds_read_b128 v[66:69], v78 offset:36928
	ds_read_b128 v[70:73], v78 offset:36960
	ds_read_b128 v[74:77], v78 offset:41536
	ds_read_b128 v[78:81], v78 offset:41568
	s_setprio 3
	v_cvt_pk_bf16_f32 v98, v185, v186
	v_cvt_pk_bf16_f32 v99, v187, v194
	v_cvt_pk_bf16_f32 v100, v195, v196
	v_cvt_pk_bf16_f32 v101, v197, v198
	s_waitcnt lgkmcnt(7)
	s_nop 0
	v_mfma_f32_32x32x16_bf16 v[18:33], v[50:53], v[98:101], v[18:33]
	v_add_f32_e32 v110, v185, v186
	v_add_f32_e32 v110, v110, v187
	v_add_f32_e32 v110, v110, v194
	s_waitcnt lgkmcnt(5)
	v_mfma_f32_32x32x16_bf16 v[2:17], v[58:61], v[98:101], v[2:17]
	v_cvt_pk_bf16_f32 v50, v199, v200
	v_cvt_pk_bf16_f32 v51, v201, v202
	v_cvt_pk_bf16_f32 v52, v122, v123
	v_cvt_pk_bf16_f32 v53, v124, v125
	v_add_f32_e32 v110, v110, v195
	v_add_f32_e32 v110, v110, v196
	v_add_f32_e32 v110, v110, v197
	v_add_f32_e32 v110, v110, v198
	s_nop 0
	v_mfma_f32_32x32x16_bf16 v[18:33], v[54:57], v[50:53], v[18:33]
	v_add_f32_e32 v110, v110, v199
	v_add_f32_e32 v110, v110, v200
	v_add_f32_e32 v110, v110, v201
	v_add_f32_e32 v110, v110, v202
	s_waitcnt lgkmcnt(4)
	v_mfma_f32_32x32x16_bf16 v[2:17], v[62:65], v[50:53], v[2:17]
	v_cvt_pk_bf16_f32 v54, v126, v127
	v_cvt_pk_bf16_f32 v55, v128, v129
	v_cvt_pk_bf16_f32 v56, v203, v204
	v_cvt_pk_bf16_f32 v57, v205, v206
	v_add_f32_e32 v110, v110, v122
	v_add_f32_e32 v110, v110, v123
	v_add_f32_e32 v110, v110, v124
	v_add_f32_e32 v110, v110, v125
	s_waitcnt lgkmcnt(3)
	v_mfma_f32_32x32x16_bf16 v[18:33], v[66:69], v[54:57], v[18:33]
	v_add_f32_e32 v110, v110, v126
	v_add_f32_e32 v110, v110, v127
	v_add_f32_e32 v110, v110, v128
	v_add_f32_e32 v110, v110, v129
	s_waitcnt lgkmcnt(1)
	v_mfma_f32_32x32x16_bf16 v[2:17], v[74:77], v[54:57], v[2:17]
	v_cvt_pk_bf16_f32 v50, v102, v103
	v_cvt_pk_bf16_f32 v51, v104, v105
	v_cvt_pk_bf16_f32 v52, v106, v107
	v_cvt_pk_bf16_f32 v53, v108, v109
	v_add_f32_e32 v110, v110, v203
	v_add_f32_e32 v110, v110, v204
	v_add_f32_e32 v110, v110, v205
	v_add_f32_e32 v110, v110, v206
	s_nop 0
	v_mfma_f32_32x32x16_bf16 v[18:33], v[70:73], v[50:53], v[18:33]
	v_add_f32_e32 v110, v110, v102
	v_add_f32_e32 v110, v110, v103
	v_add_f32_e32 v110, v110, v104
	v_add_f32_e32 v110, v110, v105
	s_waitcnt lgkmcnt(0)
	v_mfma_f32_32x32x16_bf16 v[2:17], v[78:81], v[50:53], v[2:17]
	v_add_f32_e32 v110, v110, v106
	v_add_f32_e32 v110, v110, v107
	v_add_f32_e32 v110, v110, v108
	v_add_f32_e32 v110, v110, v109
	s_setprio 2
	s_waitcnt lgkmcnt(0)
	s_barrier
	ds_read_b128 v[240:243], v165
	ds_read_b128 v[244:247], v165 offset:4608
	ds_read_b128 v[102:105], v165 offset:32
	ds_read_b128 v[106:109], v165 offset:4640
	v_add_f32_e32 v1, v1, v213
	v_exp_f32_e32 v185, v130
	v_exp_f32_e32 v186, v131
	v_exp_f32_e32 v187, v132
	v_exp_f32_e32 v194, v133
	v_exp_f32_e32 v195, v134
	v_exp_f32_e32 v196, v135
	v_exp_f32_e32 v197, v136
	v_exp_f32_e32 v198, v137
	s_waitcnt lgkmcnt(3)
	v_mfma_f32_32x32x16_bf16 v[66:81], v[240:243], v[158:161], v[34:49]
	s_waitcnt lgkmcnt(2)
	v_mfma_f32_32x32x16_bf16 v[50:65], v[244:247], v[158:161], v[34:49]
	v_exp_f32_e32 v134, v138
	v_exp_f32_e32 v135, v139
	v_exp_f32_e32 v136, v140
	v_exp_f32_e32 v137, v141
	v_exp_f32_e32 v138, v142
	v_exp_f32_e32 v139, v143
	v_exp_f32_e32 v140, v144
	v_exp_f32_e32 v141, v145
	s_waitcnt lgkmcnt(1)
	v_mfma_f32_32x32x16_bf16 v[66:81], v[102:105], v[154:157], v[66:81]
	v_exp_f32_e32 v142, v82
	v_exp_f32_e32 v143, v83
	v_exp_f32_e32 v144, v84
	v_exp_f32_e32 v145, v85
	v_exp_f32_e32 v199, v86
	v_exp_f32_e32 v200, v87
	v_exp_f32_e32 v201, v88
	v_exp_f32_e32 v202, v89
	s_waitcnt lgkmcnt(0)
	v_mfma_f32_32x32x16_bf16 v[50:65], v[106:109], v[154:157], v[50:65]
	v_exp_f32_e32 v203, v90
	v_exp_f32_e32 v204, v91
	v_exp_f32_e32 v205, v92
	v_exp_f32_e32 v206, v93
	v_exp_f32_e32 v207, v94
	v_exp_f32_e32 v208, v95
	v_exp_f32_e32 v209, v96
	v_exp_f32_e32 v210, v97
	v_add_f32_e32 v1, v1, v110
	v_add_u32_e32 v111, s26, v163
	ds_read_b128 v[240:243], v165 offset:9216
	ds_read_b128 v[244:247], v165 offset:13824
	ds_read_b128 v[82:85], v111 offset:41472
	ds_read_b128 v[86:89], v111 offset:36864
	ds_read_b128 v[90:93], v111 offset:36896
	ds_read_b128 v[94:97], v111 offset:41504
	ds_read_b128 v[98:101], v111 offset:36928
	ds_read_b128 v[102:105], v111 offset:41536
	ds_read_b128 v[106:109], v111 offset:36960
	ds_read_b128 v[110:113], v111 offset:41568
	s_cmp_gt_i32 s24, 2
	s_cselect_b32 s27, -3, 2
	s_add_i32 s27, s27, s24
	s_mulk_i32 s27, 0x2400
	v_add_u32_e32 v250, s27, v182
	s_mov_b32 s27, 0x18950000
	s_waitcnt vmcnt(3)
	ds_write_b128 v182, v[146:149] offset:18432
	s_waitcnt vmcnt(2)
	ds_write_b128 v250, v[150:153] offset:36864
	s_add_i32 s92, s23, -4
	s_lshl_b32 s92, s92, 13
	s_add_u32 vcc_lo, s100, s92
	s_addc_u32 vcc_hi, s101, 0
	global_load_dwordx4 v[126:129], v248, vcc
	s_lshl_b32 s92, s25, 7
	s_add_u32 vcc_lo, s98, s92
	s_addc_u32 vcc_hi, s99, 0
	global_load_dwordx4 v[122:125], v249, vcc
	s_add_i32 s26, s24, 1
	s_setprio 1
	v_cvt_pk_bf16_f32 v130, v185, v186
	v_cvt_pk_bf16_f32 v131, v187, v194
	v_cvt_pk_bf16_f32 v132, v195, v196
	v_cvt_pk_bf16_f32 v133, v197, v198
	s_waitcnt lgkmcnt(8)
	s_nop 0
	v_mfma_f32_32x32x16_bf16 v[18:33], v[86:89], v[130:133], v[18:33]
	v_add_f32_e32 v146, v185, v186
	v_add_f32_e32 v146, v146, v187
	v_add_f32_e32 v146, v146, v194
	s_nop 0
	v_mfma_f32_32x32x16_bf16 v[2:17], v[82:85], v[130:133], v[2:17]
	v_cvt_pk_bf16_f32 v86, v134, v135
	v_cvt_pk_bf16_f32 v87, v136, v137
	v_cvt_pk_bf16_f32 v88, v138, v139
	v_cvt_pk_bf16_f32 v89, v140, v141
	v_add_f32_e32 v146, v146, v195
	v_add_f32_e32 v146, v146, v196
	v_add_f32_e32 v146, v146, v197
	v_add_f32_e32 v146, v146, v198
	s_waitcnt lgkmcnt(7)
	v_mfma_f32_32x32x16_bf16 v[18:33], v[90:93], v[86:89], v[18:33]
	v_add_f32_e32 v146, v146, v134
	v_add_f32_e32 v146, v146, v135
	v_add_f32_e32 v146, v146, v136
	v_add_f32_e32 v146, v146, v137
	s_waitcnt lgkmcnt(6)
	v_mfma_f32_32x32x16_bf16 v[2:17], v[94:97], v[86:89], v[2:17]
	v_cvt_pk_bf16_f32 v82, v142, v143
	v_cvt_pk_bf16_f32 v83, v144, v145
	v_cvt_pk_bf16_f32 v84, v199, v200
	v_cvt_pk_bf16_f32 v85, v201, v202
	v_add_f32_e32 v146, v146, v138
	v_add_f32_e32 v146, v146, v139
	v_add_f32_e32 v146, v146, v140
	v_add_f32_e32 v146, v146, v141
	s_waitcnt lgkmcnt(5)
	v_mfma_f32_32x32x16_bf16 v[18:33], v[98:101], v[82:85], v[18:33]
	v_add_f32_e32 v146, v146, v142
	v_add_f32_e32 v146, v146, v143
	v_add_f32_e32 v146, v146, v144
	v_add_f32_e32 v146, v146, v145
	s_waitcnt lgkmcnt(4)
	v_mfma_f32_32x32x16_bf16 v[2:17], v[102:105], v[82:85], v[2:17]
	v_cvt_pk_bf16_f32 v86, v203, v204
	v_cvt_pk_bf16_f32 v87, v205, v206
	v_cvt_pk_bf16_f32 v88, v207, v208
	v_cvt_pk_bf16_f32 v89, v209, v210
	v_add_f32_e32 v146, v146, v199
	v_add_f32_e32 v146, v146, v200
	v_add_f32_e32 v146, v146, v201
	v_add_f32_e32 v146, v146, v202
	s_waitcnt lgkmcnt(3)
	v_mfma_f32_32x32x16_bf16 v[18:33], v[106:109], v[86:89], v[18:33]
	v_add_f32_e32 v146, v146, v203
	v_add_f32_e32 v146, v146, v204
	v_add_f32_e32 v146, v146, v205
	v_add_f32_e32 v146, v146, v206
	s_waitcnt lgkmcnt(2)
	v_mfma_f32_32x32x16_bf16 v[2:17], v[110:113], v[86:89], v[2:17]
	v_add_f32_e32 v146, v146, v207
	v_add_f32_e32 v146, v146, v208
	v_add_f32_e32 v146, v146, v209
	v_add_f32_e32 v146, v146, v210
	s_setprio 0
	ds_read_b128 v[130:133], v165 offset:9248
	ds_read_b128 v[138:141], v165 offset:13856
	s_cmp_lg_u32 s24, 4
	s_cselect_b32 s24, s26, 0
	s_waitcnt lgkmcnt(2)
	v_mfma_f32_32x32x16_bf16 v[98:113], v[240:243], v[158:161], v[34:49]
	v_exp_f32_e32 v142, v66
	v_exp_f32_e32 v143, v67
	v_exp_f32_e32 v144, v68
	v_exp_f32_e32 v145, v69
	v_exp_f32_e32 v147, v70
	v_exp_f32_e32 v148, v71
	v_exp_f32_e32 v149, v72
	v_exp_f32_e32 v150, v73
	s_waitcnt lgkmcnt(1)
	v_mfma_f32_32x32x16_bf16 v[82:97], v[244:247], v[158:161], v[34:49]
	v_exp_f32_e32 v151, v74
	v_exp_f32_e32 v152, v75
	v_exp_f32_e32 v153, v76
	v_exp_f32_e32 v178, v77
	v_exp_f32_e32 v134, v78
	v_exp_f32_e32 v135, v79
	v_exp_f32_e32 v136, v80
	v_exp_f32_e32 v137, v81
	v_mfma_f32_32x32x16_bf16 v[98:113], v[130:133], v[154:157], v[98:113]
	v_exp_f32_e32 v179, v50
	v_exp_f32_e32 v185, v51
	v_exp_f32_e32 v186, v52
	v_exp_f32_e32 v187, v53
	v_exp_f32_e32 v194, v54
	v_exp_f32_e32 v195, v55
	v_exp_f32_e32 v196, v56
	v_exp_f32_e32 v197, v57
	s_waitcnt lgkmcnt(0)
	v_mfma_f32_32x32x16_bf16 v[82:97], v[138:141], v[154:157], v[82:97]
	v_exp_f32_e32 v198, v58
	v_exp_f32_e32 v199, v59
	v_exp_f32_e32 v200, v60
	v_exp_f32_e32 v201, v61
	v_exp_f32_e32 v138, v62
	v_exp_f32_e32 v139, v63
	v_exp_f32_e32 v140, v64
	v_exp_f32_e32 v141, v65
	s_cmp_gt_i32 s24, 2
	s_cselect_b32 s25, -3, 2
	s_add_i32 s25, s25, s24
	s_mulk_i32 s25, 0x2400
	v_add_u32_e32 v50, s25, v182
	s_add_i32 s25, s24, 1
	s_cmp_lg_u32 s24, 4
	s_cselect_b32 s25, s25, 0
	s_add_i32 s24, s23, -3
	s_min_u32 s26, s24, s13
	s_lshl_b32 s92, s26, 13
	s_waitcnt vmcnt(3)
	ds_write_b128 v182, v[118:121] offset:27648
	s_waitcnt vmcnt(2)
	ds_write_b128 v50, v[114:117] offset:36864
	s_add_u32 vcc_lo, s100, s92
	s_addc_u32 vcc_hi, s101, 0
	global_load_dwordx4 v[118:121], v248, vcc
	s_add_i32 s92, s23, -4
	s_lshl_b32 s92, s92, 7
	s_add_u32 vcc_lo, s98, s92
	s_addc_u32 vcc_hi, s99, 0
	global_load_dwordx4 v[114:117], v249, vcc
	s_mul_i32 s27, s25, 0x2400
	s_add_i32 s28, s27, 0xffffdc00
	s_cmp_lg_u32 s25, 0
	s_cselect_b32 s28, s28, 0x9000
	v_add_u32_e32 v78, s28, v163
	ds_read_b128 v[50:53], v78 offset:36864
	ds_read_b128 v[54:57], v78 offset:36896
	ds_read_b128 v[58:61], v78 offset:41472
	ds_read_b128 v[62:65], v78 offset:41504
	ds_read_b128 v[66:69], v78 offset:36928
	ds_read_b128 v[70:73], v78 offset:36960
	ds_read_b128 v[74:77], v78 offset:41536
	ds_read_b128 v[78:81], v78 offset:41568
	s_setprio 3
	v_cvt_pk_bf16_f32 v130, v142, v143
	v_cvt_pk_bf16_f32 v131, v144, v145
	v_cvt_pk_bf16_f32 v132, v147, v148
	v_cvt_pk_bf16_f32 v133, v149, v150
	s_waitcnt lgkmcnt(7)
	s_nop 0
	v_mfma_f32_32x32x16_bf16 v[18:33], v[50:53], v[130:133], v[18:33]
	v_add_f32_e32 v176, v142, v143
	v_add_f32_e32 v176, v176, v144
	v_add_f32_e32 v176, v176, v145
	s_waitcnt lgkmcnt(5)
	v_mfma_f32_32x32x16_bf16 v[2:17], v[58:61], v[130:133], v[2:17]
	v_cvt_pk_bf16_f32 v50, v151, v152
	v_cvt_pk_bf16_f32 v51, v153, v178
	v_cvt_pk_bf16_f32 v52, v134, v135
	v_cvt_pk_bf16_f32 v53, v136, v137
	v_add_f32_e32 v176, v176, v147
	v_add_f32_e32 v176, v176, v148
	v_add_f32_e32 v176, v176, v149
	v_add_f32_e32 v176, v176, v150
	s_nop 0
	v_mfma_f32_32x32x16_bf16 v[18:33], v[54:57], v[50:53], v[18:33]
	v_add_f32_e32 v176, v176, v151
	v_add_f32_e32 v176, v176, v152
	v_add_f32_e32 v176, v176, v153
	v_add_f32_e32 v176, v176, v178
	s_waitcnt lgkmcnt(4)
	v_mfma_f32_32x32x16_bf16 v[2:17], v[62:65], v[50:53], v[2:17]
	v_cvt_pk_bf16_f32 v54, v179, v185
	v_cvt_pk_bf16_f32 v55, v186, v187
	v_cvt_pk_bf16_f32 v56, v194, v195
	v_cvt_pk_bf16_f32 v57, v196, v197
	v_add_f32_e32 v176, v176, v134
	v_add_f32_e32 v176, v176, v135
	v_add_f32_e32 v176, v176, v136
	v_add_f32_e32 v176, v176, v137
	s_waitcnt lgkmcnt(3)
	v_mfma_f32_32x32x16_bf16 v[18:33], v[66:69], v[54:57], v[18:33]
	v_add_f32_e32 v176, v176, v179
	v_add_f32_e32 v176, v176, v185
	v_add_f32_e32 v176, v176, v186
	v_add_f32_e32 v176, v176, v187
	s_waitcnt lgkmcnt(1)
	v_mfma_f32_32x32x16_bf16 v[2:17], v[74:77], v[54:57], v[2:17]
	v_cvt_pk_bf16_f32 v50, v198, v199
	v_cvt_pk_bf16_f32 v51, v200, v201
	v_cvt_pk_bf16_f32 v52, v138, v139
	v_cvt_pk_bf16_f32 v53, v140, v141
	v_add_f32_e32 v176, v176, v194
	v_add_f32_e32 v176, v176, v195
	v_add_f32_e32 v176, v176, v196
	v_add_f32_e32 v176, v176, v197
	s_nop 0
	v_mfma_f32_32x32x16_bf16 v[18:33], v[70:73], v[50:53], v[18:33]
	v_add_f32_e32 v176, v176, v198
	v_add_f32_e32 v176, v176, v199
	v_add_f32_e32 v176, v176, v200
	v_add_f32_e32 v176, v176, v201
	s_waitcnt lgkmcnt(0)
	v_mfma_f32_32x32x16_bf16 v[2:17], v[78:81], v[50:53], v[2:17]
	v_add_f32_e32 v176, v176, v138
	v_add_f32_e32 v176, v176, v139
	v_add_f32_e32 v176, v176, v140
	v_add_f32_e32 v176, v176, v141
	s_setprio 2
	s_waitcnt lgkmcnt(0)
	s_barrier
	ds_read_b128 v[240:243], v165 offset:18432
	ds_read_b128 v[244:247], v165 offset:23040
	ds_read_b128 v[134:137], v165 offset:18464
	ds_read_b128 v[138:141], v165 offset:23072
	v_add_f32_e32 v1, v1, v146
	v_exp_f32_e32 v142, v98
	v_exp_f32_e32 v143, v99
	v_exp_f32_e32 v144, v100
	v_exp_f32_e32 v145, v101
	v_exp_f32_e32 v146, v102
	v_exp_f32_e32 v147, v103
	v_exp_f32_e32 v148, v104
	v_exp_f32_e32 v149, v105
	s_waitcnt lgkmcnt(3)
	v_mfma_f32_32x32x16_bf16 v[66:81], v[240:243], v[158:161], v[34:49]
	s_waitcnt lgkmcnt(2)
	v_mfma_f32_32x32x16_bf16 v[50:65], v[244:247], v[158:161], v[34:49]
	v_exp_f32_e32 v150, v106
	v_exp_f32_e32 v151, v107
	v_exp_f32_e32 v152, v108
	v_exp_f32_e32 v153, v109
	v_exp_f32_e32 v177, v110
	v_exp_f32_e32 v178, v111
	v_exp_f32_e32 v179, v112
	v_exp_f32_e32 v185, v113
	s_waitcnt lgkmcnt(1)
	v_mfma_f32_32x32x16_bf16 v[66:81], v[134:137], v[154:157], v[66:81]
	v_exp_f32_e32 v186, v82
	v_exp_f32_e32 v187, v83
	v_exp_f32_e32 v194, v84
	v_exp_f32_e32 v195, v85
	v_exp_f32_e32 v134, v86
	v_exp_f32_e32 v135, v87
	v_exp_f32_e32 v136, v88
	v_exp_f32_e32 v137, v89
	s_waitcnt lgkmcnt(0)
	v_mfma_f32_32x32x16_bf16 v[50:65], v[138:141], v[154:157], v[50:65]
	v_exp_f32_e32 v196, v90
	v_exp_f32_e32 v197, v91
	v_exp_f32_e32 v198, v92
	v_exp_f32_e32 v199, v93
	v_exp_f32_e32 v138, v94
	v_exp_f32_e32 v139, v95
	v_exp_f32_e32 v140, v96
	v_exp_f32_e32 v141, v97
	s_cmp_gt_i32 s25, 2
	s_cselect_b32 s28, -3, 2
	s_waitcnt vmcnt(3)
	ds_write_b128 v182, v[126:129]
	s_add_i32 s28, s28, s25
	v_add_u32_e32 v126, s27, v163
	s_add_i32 s27, s23, -2
	s_mulk_i32 s28, 0x2400
	s_min_u32 s27, s27, s13
	v_add_u32_e32 v82, s28, v182
	s_lshl_b32 s92, s27, 13
	s_waitcnt vmcnt(2)
	ds_write_b128 v82, v[122:125] offset:36864
	ds_read_b128 v[240:243], v165 offset:27648
	ds_read_b128 v[244:247], v165 offset:32256
	ds_read_b128 v[82:85], v126 offset:41472
	ds_read_b128 v[86:89], v126 offset:36864
	ds_read_b128 v[90:93], v126 offset:36896
	ds_read_b128 v[94:97], v126 offset:41504
	ds_read_b128 v[106:109], v126 offset:36928
	ds_read_b128 v[110:113], v126 offset:41536
	ds_read_b128 v[122:125], v126 offset:36960
	ds_read_b128 v[126:129], v126 offset:41568
	s_add_u32 vcc_lo, s100, s92
	s_addc_u32 vcc_hi, s101, 0
	global_load_dwordx4 v[98:101], v248, vcc
	s_lshl_b32 s92, s26, 7
	s_add_u32 vcc_lo, s98, s92
	s_addc_u32 vcc_hi, s99, 0
	global_load_dwordx4 v[102:105], v249, vcc
	v_add_f32_e32 v1, v1, v176
	s_add_i32 s28, s25, 1
	s_setprio 1
	v_cvt_pk_bf16_f32 v130, v142, v143
	v_cvt_pk_bf16_f32 v131, v144, v145
	v_cvt_pk_bf16_f32 v132, v146, v147
	v_cvt_pk_bf16_f32 v133, v148, v149
	s_waitcnt lgkmcnt(6)
	s_nop 0
	v_mfma_f32_32x32x16_bf16 v[18:33], v[86:89], v[130:133], v[18:33]
	v_add_f32_e32 v176, v142, v143
	v_add_f32_e32 v176, v176, v144
	v_add_f32_e32 v176, v176, v145
	s_nop 0
	v_mfma_f32_32x32x16_bf16 v[2:17], v[82:85], v[130:133], v[2:17]
	v_cvt_pk_bf16_f32 v86, v150, v151
	v_cvt_pk_bf16_f32 v87, v152, v153
	v_cvt_pk_bf16_f32 v88, v177, v178
	v_cvt_pk_bf16_f32 v89, v179, v185
	v_add_f32_e32 v176, v176, v146
	v_add_f32_e32 v176, v176, v147
	v_add_f32_e32 v176, v176, v148
	v_add_f32_e32 v176, v176, v149
	s_waitcnt lgkmcnt(5)
	v_mfma_f32_32x32x16_bf16 v[18:33], v[90:93], v[86:89], v[18:33]
	v_add_f32_e32 v176, v176, v150
	v_add_f32_e32 v176, v176, v151
	v_add_f32_e32 v176, v176, v152
	v_add_f32_e32 v176, v176, v153
	s_waitcnt lgkmcnt(4)
	v_mfma_f32_32x32x16_bf16 v[2:17], v[94:97], v[86:89], v[2:17]
	v_cvt_pk_bf16_f32 v82, v186, v187
	v_cvt_pk_bf16_f32 v83, v194, v195
	v_cvt_pk_bf16_f32 v84, v134, v135
	v_cvt_pk_bf16_f32 v85, v136, v137
	v_add_f32_e32 v176, v176, v177
	v_add_f32_e32 v176, v176, v178
	v_add_f32_e32 v176, v176, v179
	v_add_f32_e32 v176, v176, v185
	s_waitcnt lgkmcnt(3)
	v_mfma_f32_32x32x16_bf16 v[18:33], v[106:109], v[82:85], v[18:33]
	v_add_f32_e32 v176, v176, v186
	v_add_f32_e32 v176, v176, v187
	v_add_f32_e32 v176, v176, v194
	v_add_f32_e32 v176, v176, v195
	s_waitcnt lgkmcnt(2)
	v_mfma_f32_32x32x16_bf16 v[2:17], v[110:113], v[82:85], v[2:17]
	v_cvt_pk_bf16_f32 v86, v196, v197
	v_cvt_pk_bf16_f32 v87, v198, v199
	v_cvt_pk_bf16_f32 v88, v138, v139
	v_cvt_pk_bf16_f32 v89, v140, v141
	v_add_f32_e32 v176, v176, v134
	v_add_f32_e32 v176, v176, v135
	v_add_f32_e32 v176, v176, v136
	v_add_f32_e32 v176, v176, v137
	s_waitcnt lgkmcnt(1)
	v_mfma_f32_32x32x16_bf16 v[18:33], v[122:125], v[86:89], v[18:33]
	v_add_f32_e32 v176, v176, v196
	v_add_f32_e32 v176, v176, v197
	v_add_f32_e32 v176, v176, v198
	v_add_f32_e32 v176, v176, v199
	s_waitcnt lgkmcnt(0)
	v_mfma_f32_32x32x16_bf16 v[2:17], v[126:129], v[86:89], v[2:17]
	v_add_f32_e32 v176, v176, v138
	v_add_f32_e32 v176, v176, v139
	v_add_f32_e32 v176, v176, v140
	v_add_f32_e32 v176, v176, v141
	s_setprio 0
	ds_read_b128 v[106:109], v165 offset:27680
	ds_read_b128 v[122:125], v165 offset:32288
	s_cmp_lg_u32 s25, 4
	s_cselect_b32 s25, s28, 0
	s_waitcnt lgkmcnt(2)
	v_mfma_f32_32x32x16_bf16 v[138:153], v[240:243], v[158:161], v[34:49]
	v_exp_f32_e32 v126, v66
	v_exp_f32_e32 v127, v67
	v_exp_f32_e32 v128, v68
	v_exp_f32_e32 v129, v69
	v_exp_f32_e32 v130, v70
	v_exp_f32_e32 v131, v71
	v_exp_f32_e32 v132, v72
	v_exp_f32_e32 v133, v73
	s_waitcnt lgkmcnt(1)
	v_mfma_f32_32x32x16_bf16 v[82:97], v[244:247], v[158:161], v[34:49]
	v_exp_f32_e32 v134, v74
	v_exp_f32_e32 v135, v75
	v_exp_f32_e32 v136, v76
	v_exp_f32_e32 v137, v77
	v_exp_f32_e32 v177, v78
	v_exp_f32_e32 v178, v79
	v_exp_f32_e32 v179, v80
	v_exp_f32_e32 v185, v81
	v_mfma_f32_32x32x16_bf16 v[138:153], v[106:109], v[154:157], v[138:153]
	v_exp_f32_e32 v80, v50
	v_exp_f32_e32 v81, v51
	v_exp_f32_e32 v186, v52
	v_exp_f32_e32 v187, v53
	v_exp_f32_e32 v194, v54
	v_exp_f32_e32 v195, v55
	v_exp_f32_e32 v196, v56
	v_exp_f32_e32 v197, v57
	s_waitcnt lgkmcnt(0)
	v_mfma_f32_32x32x16_bf16 v[82:97], v[122:125], v[154:157], v[82:97]
	v_exp_f32_e32 v198, v58
	v_exp_f32_e32 v199, v59
	v_exp_f32_e32 v200, v60
	v_exp_f32_e32 v201, v61
	v_exp_f32_e32 v122, v62
	v_exp_f32_e32 v123, v63
	v_exp_f32_e32 v124, v64
	v_exp_f32_e32 v125, v65
	s_cmp_gt_i32 s25, 2
	s_cselect_b32 s26, -3, 2
	s_add_i32 s26, s26, s25
	s_mulk_i32 s26, 0x2400
	v_add_u32_e32 v50, s26, v182
	s_add_i32 s26, s25, 1
	s_cmp_lg_u32 s25, 4
	s_cselect_b32 s25, s26, 0
	s_add_i32 s26, s23, -1
	s_min_u32 s26, s26, s13
	s_lshl_b32 s92, s26, 13
	s_waitcnt vmcnt(3)
	ds_write_b128 v182, v[118:121] offset:9216
	s_waitcnt vmcnt(2)
	ds_write_b128 v50, v[114:117] offset:36864
	s_add_u32 vcc_lo, s100, s92
	s_addc_u32 vcc_hi, s101, 0
	global_load_dwordx4 v[56:59], v248, vcc
	s_lshl_b32 s92, s27, 7
	s_add_u32 vcc_lo, s98, s92
	s_addc_u32 vcc_hi, s99, 0
	global_load_dwordx4 v[52:55], v249, vcc
	s_nop 0
	s_mul_i32 s27, s25, 0x2400
	s_add_i32 s28, s27, 0xffffdc00
	s_cmp_lg_u32 s25, 0
	s_cselect_b32 s28, s28, 0x9000
	v_add_u32_e32 v50, s28, v163
	ds_read_b128 v[60:63], v50 offset:36864
	ds_read_b128 v[64:67], v50 offset:36896
	ds_read_b128 v[68:71], v50 offset:41472
	ds_read_b128 v[72:75], v50 offset:41504
	ds_read_b128 v[76:79], v50 offset:36928
	ds_read_b128 v[106:109], v50 offset:36960
	ds_read_b128 v[110:113], v50 offset:41536
	ds_read_b128 v[114:117], v50 offset:41568
	s_setprio 3
	v_cvt_pk_bf16_f32 v118, v126, v127
	v_cvt_pk_bf16_f32 v119, v128, v129
	v_cvt_pk_bf16_f32 v120, v130, v131
	v_cvt_pk_bf16_f32 v121, v132, v133
	s_waitcnt lgkmcnt(7)
	s_nop 0
	v_mfma_f32_32x32x16_bf16 v[18:33], v[60:63], v[118:121], v[18:33]
	v_add_f32_e32 v50, v126, v127
	v_add_f32_e32 v50, v50, v128
	v_add_f32_e32 v50, v50, v129
	s_waitcnt lgkmcnt(5)
	v_mfma_f32_32x32x16_bf16 v[2:17], v[68:71], v[118:121], v[2:17]
	v_cvt_pk_bf16_f32 v60, v134, v135
	v_cvt_pk_bf16_f32 v61, v136, v137
	v_cvt_pk_bf16_f32 v62, v177, v178
	v_cvt_pk_bf16_f32 v63, v179, v185
	v_add_f32_e32 v50, v50, v130
	v_add_f32_e32 v50, v50, v131
	v_add_f32_e32 v50, v50, v132
	v_add_f32_e32 v50, v50, v133
	s_nop 0
	v_mfma_f32_32x32x16_bf16 v[18:33], v[64:67], v[60:63], v[18:33]
	v_add_f32_e32 v50, v50, v134
	v_add_f32_e32 v50, v50, v135
	v_add_f32_e32 v50, v50, v136
	v_add_f32_e32 v50, v50, v137
	s_waitcnt lgkmcnt(4)
	v_mfma_f32_32x32x16_bf16 v[2:17], v[72:75], v[60:63], v[2:17]
	v_cvt_pk_bf16_f32 v64, v80, v81
	v_cvt_pk_bf16_f32 v65, v186, v187
	v_cvt_pk_bf16_f32 v66, v194, v195
	v_cvt_pk_bf16_f32 v67, v196, v197
	v_add_f32_e32 v50, v50, v177
	v_add_f32_e32 v50, v50, v178
	v_add_f32_e32 v50, v50, v179
	v_add_f32_e32 v50, v50, v185
	s_waitcnt lgkmcnt(3)
	v_mfma_f32_32x32x16_bf16 v[18:33], v[76:79], v[64:67], v[18:33]
	v_add_f32_e32 v50, v50, v80
	v_add_f32_e32 v50, v50, v81
	v_add_f32_e32 v50, v50, v186
	v_add_f32_e32 v50, v50, v187
	s_waitcnt lgkmcnt(1)
	v_mfma_f32_32x32x16_bf16 v[2:17], v[110:113], v[64:67], v[2:17]
	v_cvt_pk_bf16_f32 v60, v198, v199
	v_cvt_pk_bf16_f32 v61, v200, v201
	v_cvt_pk_bf16_f32 v62, v122, v123
	v_cvt_pk_bf16_f32 v63, v124, v125
	v_add_f32_e32 v50, v50, v194
	v_add_f32_e32 v50, v50, v195
	v_add_f32_e32 v50, v50, v196
	v_add_f32_e32 v50, v50, v197
	s_nop 0
	v_mfma_f32_32x32x16_bf16 v[18:33], v[106:109], v[60:63], v[18:33]
	v_add_f32_e32 v50, v50, v198
	v_add_f32_e32 v50, v50, v199
	v_add_f32_e32 v50, v50, v200
	v_add_f32_e32 v50, v50, v201
	s_waitcnt lgkmcnt(0)
	v_mfma_f32_32x32x16_bf16 v[2:17], v[114:117], v[60:63], v[2:17]
	v_add_f32_e32 v50, v50, v122
	v_add_f32_e32 v50, v50, v123
	v_add_f32_e32 v50, v50, v124
	v_add_f32_e32 v50, v50, v125
	s_setprio 2
	s_waitcnt lgkmcnt(0)
	s_barrier
	ds_read_b128 v[240:243], v165
	ds_read_b128 v[244:247], v165 offset:4608
	ds_read_b128 v[68:71], v165 offset:32
	ds_read_b128 v[72:75], v165 offset:4640
	v_add_f32_e32 v1, v1, v176
	v_exp_f32_e32 v176, v138
	v_exp_f32_e32 v177, v139
	v_exp_f32_e32 v178, v140
	v_exp_f32_e32 v179, v141
	v_exp_f32_e32 v185, v142
	v_exp_f32_e32 v186, v143
	v_exp_f32_e32 v187, v144
	v_exp_f32_e32 v194, v145
	s_waitcnt lgkmcnt(3)
	v_mfma_f32_32x32x16_bf16 v[122:137], v[240:243], v[158:161], v[34:49]
	s_waitcnt lgkmcnt(2)
	v_mfma_f32_32x32x16_bf16 v[106:121], v[244:247], v[158:161], v[34:49]
	v_exp_f32_e32 v195, v146
	v_exp_f32_e32 v196, v147
	v_exp_f32_e32 v197, v148
	v_exp_f32_e32 v198, v149
	v_exp_f32_e32 v146, v150
	v_exp_f32_e32 v147, v151
	v_exp_f32_e32 v148, v152
	v_exp_f32_e32 v149, v153
	s_waitcnt lgkmcnt(1)
	v_mfma_f32_32x32x16_bf16 v[122:137], v[68:71], v[154:157], v[122:137]
	v_exp_f32_e32 v150, v82
	v_exp_f32_e32 v151, v83
	v_exp_f32_e32 v152, v84
	v_exp_f32_e32 v153, v85
	v_exp_f32_e32 v199, v86
	v_exp_f32_e32 v200, v87
	v_exp_f32_e32 v201, v88
	v_exp_f32_e32 v202, v89
	s_waitcnt lgkmcnt(0)
	v_mfma_f32_32x32x16_bf16 v[106:121], v[72:75], v[154:157], v[106:121]
	v_exp_f32_e32 v203, v90
	v_exp_f32_e32 v204, v91
	v_exp_f32_e32 v205, v92
	v_exp_f32_e32 v206, v93
	v_exp_f32_e32 v207, v94
	v_exp_f32_e32 v208, v95
	v_exp_f32_e32 v209, v96
	v_exp_f32_e32 v210, v97
	v_add_u32_e32 v88, s27, v163
	ds_read_b128 v[240:243], v165 offset:9216
	ds_read_b128 v[244:247], v165 offset:13824
	ds_read_b128 v[60:63], v88 offset:41472
	ds_read_b128 v[64:67], v88 offset:36864
	ds_read_b128 v[68:71], v88 offset:36896
	ds_read_b128 v[72:75], v88 offset:41504
	ds_read_b128 v[76:79], v88 offset:36928
	ds_read_b128 v[80:83], v88 offset:41536
	ds_read_b128 v[84:87], v88 offset:36960
	ds_read_b128 v[88:91], v88 offset:41568
	s_cmp_gt_i32 s25, 2
	s_cselect_b32 s28, -3, 2
	s_add_i32 s28, s28, s25
	s_mulk_i32 s28, 0x2400
	s_min_u32 s27, s23, s13
	v_add_u32_e32 v51, s28, v182
	s_lshl_b32 s92, s27, 13
	s_waitcnt vmcnt(3)
	ds_write_b128 v182, v[98:101] offset:18432
	s_waitcnt vmcnt(2)
	ds_write_b128 v51, v[102:105] offset:36864
	v_add_f32_e32 v1, v1, v50
	s_add_u32 vcc_lo, s100, s92
	s_addc_u32 vcc_hi, s101, 0
	global_load_dwordx4 v[138:141], v248, vcc
	s_lshl_b32 s92, s26, 7
	s_add_u32 vcc_lo, s98, s92
	s_addc_u32 vcc_hi, s99, 0
	global_load_dwordx4 v[142:145], v249, vcc
	s_setprio 1
	v_mov_b32_e32 v51, v122
	v_cvt_pk_bf16_f32 v92, v176, v177
	v_cvt_pk_bf16_f32 v93, v178, v179
	v_cvt_pk_bf16_f32 v94, v185, v186
	v_cvt_pk_bf16_f32 v95, v187, v194
	s_waitcnt lgkmcnt(8)
	s_nop 0
	v_mfma_f32_32x32x16_bf16 v[18:33], v[64:67], v[92:95], v[18:33]
	v_max3_f32 v51, v51, v123, v124
	v_max3_f32 v51, v51, v125, v126
	v_add_f32_e32 v50, v176, v177
	v_add_f32_e32 v50, v50, v178
	v_add_f32_e32 v50, v50, v179
	s_nop 0
	v_mfma_f32_32x32x16_bf16 v[2:17], v[60:63], v[92:95], v[2:17]
	v_cvt_pk_bf16_f32 v64, v195, v196
	v_cvt_pk_bf16_f32 v65, v197, v198
	v_cvt_pk_bf16_f32 v66, v146, v147
	v_cvt_pk_bf16_f32 v67, v148, v149
	v_max3_f32 v51, v51, v127, v128
	v_max3_f32 v51, v51, v129, v130
	v_add_f32_e32 v50, v50, v185
	v_add_f32_e32 v50, v50, v186
	v_add_f32_e32 v50, v50, v187
	v_add_f32_e32 v50, v50, v194
	s_waitcnt lgkmcnt(7)
	v_mfma_f32_32x32x16_bf16 v[18:33], v[68:71], v[64:67], v[18:33]
	v_max3_f32 v51, v51, v131, v132
	v_max3_f32 v51, v51, v133, v134
	v_add_f32_e32 v50, v50, v195
	v_add_f32_e32 v50, v50, v196
	v_add_f32_e32 v50, v50, v197
	v_add_f32_e32 v50, v50, v198
	s_waitcnt lgkmcnt(6)
	v_mfma_f32_32x32x16_bf16 v[2:17], v[72:75], v[64:67], v[2:17]
	v_cvt_pk_bf16_f32 v60, v150, v151
	v_cvt_pk_bf16_f32 v61, v152, v153
	v_cvt_pk_bf16_f32 v62, v199, v200
	v_cvt_pk_bf16_f32 v63, v201, v202
	v_max3_f32 v51, v51, v135, v136
	v_max3_f32 v51, v51, v137, v106
	v_add_f32_e32 v50, v50, v146
	v_add_f32_e32 v50, v50, v147
	v_add_f32_e32 v50, v50, v148
	v_add_f32_e32 v50, v50, v149
	s_waitcnt lgkmcnt(5)
	v_mfma_f32_32x32x16_bf16 v[18:33], v[76:79], v[60:63], v[18:33]
	v_max3_f32 v51, v51, v107, v108
	v_max3_f32 v51, v51, v109, v110
	v_add_f32_e32 v50, v50, v150
	v_add_f32_e32 v50, v50, v151
	v_add_f32_e32 v50, v50, v152
	v_add_f32_e32 v50, v50, v153
	s_waitcnt lgkmcnt(4)
	v_mfma_f32_32x32x16_bf16 v[2:17], v[80:83], v[60:63], v[2:17]
	v_cvt_pk_bf16_f32 v64, v203, v204
	v_cvt_pk_bf16_f32 v65, v205, v206
	v_cvt_pk_bf16_f32 v66, v207, v208
	v_cvt_pk_bf16_f32 v67, v209, v210
	v_max3_f32 v51, v51, v111, v112
	v_max3_f32 v51, v51, v113, v114
	v_add_f32_e32 v50, v50, v199
	v_add_f32_e32 v50, v50, v200
	v_add_f32_e32 v50, v50, v201
	v_add_f32_e32 v50, v50, v202
	s_waitcnt lgkmcnt(3)
	v_mfma_f32_32x32x16_bf16 v[18:33], v[84:87], v[64:67], v[18:33]
	v_max3_f32 v51, v51, v115, v116
	v_max3_f32 v51, v51, v117, v118
	v_add_f32_e32 v50, v50, v203
	v_add_f32_e32 v50, v50, v204
	v_add_f32_e32 v50, v50, v205
	v_add_f32_e32 v50, v50, v206
	s_waitcnt lgkmcnt(2)
	v_mfma_f32_32x32x16_bf16 v[2:17], v[88:91], v[64:67], v[2:17]
	v_max3_f32 v51, v51, v119, v120
	v_max3_f32 v51, v51, v121, v121
	v_add_f32_e32 v50, v50, v207
	v_add_f32_e32 v50, v50, v208
	v_add_f32_e32 v50, v50, v209
	v_add_f32_e32 v50, v50, v210
	s_setprio 0
	ds_read_b128 v[146:149], v165 offset:9248
	ds_read_b128 v[60:63], v165 offset:13856
	v_add_f32_e32 v50, v1, v50
	v_mov_b32_e32 v1, v51
	s_nop 1
	v_permlane32_swap_b32_e32 v51, v1
	v_max_f32_e32 v1, v1, v1
	v_max_f32_e32 v51, v51, v51
	v_max_f32_e32 v1, v51, v1
	v_cmp_lt_f32_e32 vcc, s52, v1
	s_cbranch_vccz .LBB0_643
	v_max_f32_e32 v1, v1, v1
	v_max_f32_e32 v68, 0, v1
	v_add_f32_e32 v183, v183, v68
	v_xor_b32_e32 v34, 0x80000000, v183
	v_pk_add_f32 v[122:123], v[122:123], v[68:69] op_sel_hi:[1,0] neg_lo:[0,1] neg_hi:[0,1]
	v_pk_add_f32 v[106:107], v[106:107], v[68:69] op_sel_hi:[1,0] neg_lo:[0,1] neg_hi:[0,1]
	v_pk_add_f32 v[124:125], v[124:125], v[68:69] op_sel_hi:[1,0] neg_lo:[0,1] neg_hi:[0,1]
	v_pk_add_f32 v[108:109], v[108:109], v[68:69] op_sel_hi:[1,0] neg_lo:[0,1] neg_hi:[0,1]
	v_pk_add_f32 v[126:127], v[126:127], v[68:69] op_sel_hi:[1,0] neg_lo:[0,1] neg_hi:[0,1]
	v_pk_add_f32 v[110:111], v[110:111], v[68:69] op_sel_hi:[1,0] neg_lo:[0,1] neg_hi:[0,1]
	v_pk_add_f32 v[128:129], v[128:129], v[68:69] op_sel_hi:[1,0] neg_lo:[0,1] neg_hi:[0,1]
	v_pk_add_f32 v[112:113], v[112:113], v[68:69] op_sel_hi:[1,0] neg_lo:[0,1] neg_hi:[0,1]
	v_pk_add_f32 v[130:131], v[130:131], v[68:69] op_sel_hi:[1,0] neg_lo:[0,1] neg_hi:[0,1]
	v_pk_add_f32 v[114:115], v[114:115], v[68:69] op_sel_hi:[1,0] neg_lo:[0,1] neg_hi:[0,1]
	v_pk_add_f32 v[132:133], v[132:133], v[68:69] op_sel_hi:[1,0] neg_lo:[0,1] neg_hi:[0,1]
	v_pk_add_f32 v[116:117], v[116:117], v[68:69] op_sel_hi:[1,0] neg_lo:[0,1] neg_hi:[0,1]
	v_pk_add_f32 v[134:135], v[134:135], v[68:69] op_sel_hi:[1,0] neg_lo:[0,1] neg_hi:[0,1]
	v_pk_add_f32 v[118:119], v[118:119], v[68:69] op_sel_hi:[1,0] neg_lo:[0,1] neg_hi:[0,1]
	v_pk_add_f32 v[136:137], v[136:137], v[68:69] op_sel_hi:[1,0] neg_lo:[0,1] neg_hi:[0,1]
	v_pk_add_f32 v[120:121], v[120:121], v[68:69] op_sel_hi:[1,0] neg_lo:[0,1] neg_hi:[0,1]
	v_exp_f32_e64 v68, -v68
	v_mov_b32_e32 v35, v34
	v_mov_b32_e32 v36, v34
	v_mov_b32_e32 v37, v34
	v_mov_b32_e32 v38, v34
	v_mov_b32_e32 v39, v34
	v_mov_b32_e32 v40, v34
	v_mov_b32_e32 v41, v34
	v_mov_b32_e32 v42, v34
	v_mov_b32_e32 v43, v34
	v_mov_b32_e32 v44, v34
	v_mov_b32_e32 v45, v34
	v_mov_b32_e32 v46, v34
	v_mov_b32_e32 v47, v34
	v_mov_b32_e32 v48, v34
	v_mov_b32_e32 v49, v34
	s_nop 11
	v_pk_mul_f32 v[32:33], v[32:33], v[68:69] op_sel_hi:[1,0]
	v_pk_mul_f32 v[30:31], v[30:31], v[68:69] op_sel_hi:[1,0]
	v_pk_mul_f32 v[28:29], v[28:29], v[68:69] op_sel_hi:[1,0]
	v_pk_mul_f32 v[26:27], v[26:27], v[68:69] op_sel_hi:[1,0]
	v_pk_mul_f32 v[24:25], v[24:25], v[68:69] op_sel_hi:[1,0]
	v_pk_mul_f32 v[22:23], v[22:23], v[68:69] op_sel_hi:[1,0]
	v_pk_mul_f32 v[20:21], v[20:21], v[68:69] op_sel_hi:[1,0]
	v_pk_mul_f32 v[18:19], v[18:19], v[68:69] op_sel_hi:[1,0]
	v_pk_mul_f32 v[16:17], v[16:17], v[68:69] op_sel_hi:[1,0]
	v_pk_mul_f32 v[14:15], v[14:15], v[68:69] op_sel_hi:[1,0]
	v_pk_mul_f32 v[12:13], v[12:13], v[68:69] op_sel_hi:[1,0]
	v_pk_mul_f32 v[10:11], v[10:11], v[68:69] op_sel_hi:[1,0]
	v_pk_mul_f32 v[8:9], v[8:9], v[68:69] op_sel_hi:[1,0]
	v_pk_mul_f32 v[6:7], v[6:7], v[68:69] op_sel_hi:[1,0]
	v_pk_mul_f32 v[4:5], v[4:5], v[68:69] op_sel_hi:[1,0]
	v_pk_mul_f32 v[2:3], v[2:3], v[68:69] op_sel_hi:[1,0]
	v_mul_f32_e32 v50, v50, v68
